# strategy 8 (fill LDS latency shadow): phase-3 triangular solve issues the LDS reads of rows 2 and 3 together with row 1 at block entry (into registers the block overwrites later), counted lgkmcnt wait
# speedup vs baseline: 1.0001x; 1.0001x over previous
.LBB0_355:
	s_and_b64 vcc, exec, s[18:19]
	s_cbranch_vccz .LBB0_421
	v_add_u32_e32 v2, v171, v187
	ds_read_b128 v[4:7], v2 offset:272
	v_mov_b32_e32 v2, v188
	ds_read_b128 v[18:21], v2 offset:544
	ds_read_b128 v[22:25], v2 offset:816
	s_waitcnt lgkmcnt(2)
	v_fma_f32 v17, -v195, v4, v196
	v_add_u32_e32 v3, 0, v2
	s_nop 0
	v_add_u32_e32 v3, 0, v2
	s_waitcnt lgkmcnt(1)
	v_fma_f32 v3, -v195, v18, v197
	v_fma_f32 v4, -v19, v17, 0
	v_add_f32_e32 v15, v4, v3
	s_nop 0
	v_add_u32_e32 v3, 0, v2
	ds_read_b128 v[4:7], v3 offset:1088
	s_waitcnt lgkmcnt(1)
	v_fma_f32 v3, -v195, v22, v198
	v_fma_f32 v8, -v17, v23, 0
	v_fma_f32 v9, -v24, v15, 0
	v_add_f32_e32 v3, v8, v3
	v_add_f32_e32 v13, v9, v3
	s_nop 0
	v_add_u32_e32 v3, 0, v2
	ds_read_b128 v[18:21], v3 offset:1360
	ds_read_b128 v[8:11], v3 offset:1376
	s_waitcnt lgkmcnt(2)
	v_fma_f32 v3, -v195, v4, v199
	v_fma_f32 v4, -v17, v5, 0
	v_fma_f32 v5, -v15, v6, 0
	v_fma_f32 v6, -v7, v13, 0
	v_add_f32_e32 v3, v4, v3
	v_add_f32_e32 v4, v6, v5
	s_waitcnt lgkmcnt(0)
	v_add_f32_e32 v11, v4, v3
	v_fma_f32 v9, -v17, v19, 0
	v_add_u32_e32 v3, 0, v2
	ds_read_b128 v[4:7], v3 offset:1632
	ds_read_b128 v[22:25], v3 offset:1648
	v_fma_f32 v3, -v195, v18, v200
	v_fma_f32 v10, -v15, v20, 0
	v_fma_f32 v12, -v13, v21, 0
	v_fma_f32 v3, -v8, v11, v3
	v_add_f32_e32 v3, v9, v3
	v_add_f32_e32 v8, v12, v10
	v_add_f32_e32 v9, v8, v3
	s_nop 0
	v_add_u32_e32 v3, 0, v2
	ds_read_b128 v[18:21], v3 offset:1904
	ds_read_b128 v[28:31], v3 offset:1920
	s_waitcnt lgkmcnt(3)
	v_fma_f32 v3, -v195, v4, v201
	v_fma_f32 v4, -v17, v5, 0
	v_fma_f32 v5, -v15, v6, 0
	v_fma_f32 v6, -v13, v7, 0
	s_waitcnt lgkmcnt(2)
	v_fma_f32 v3, -v11, v22, v3
	v_fma_f32 v4, -v23, v9, v4
	v_add_f32_e32 v3, v4, v3
	v_add_f32_e32 v4, v6, v5
	v_add_f32_e32 v7, v4, v3
	s_waitcnt lgkmcnt(1)
	v_fma_f32 v4, -v17, v19, 0
	v_add_u32_e32 v3, 0, v2
	ds_read_b128 v[22:25], v3 offset:2176
	ds_read_b128 v[32:35], v3 offset:2192
	v_fma_f32 v3, -v195, v18, v202
	v_fma_f32 v5, -v15, v20, 0
	v_fma_f32 v6, -v13, v21, 0
	s_waitcnt lgkmcnt(2)
	v_fma_f32 v3, -v11, v28, v3
	v_fma_f32 v4, -v9, v29, v4
	v_fma_f32 v5, -v30, v7, v5
	v_add_f32_e32 v3, v4, v3
	v_add_f32_e32 v4, v6, v5
	v_add_f32_e32 v4, v4, v3
	s_waitcnt lgkmcnt(1)
	v_fma_f32 v5, -v17, v23, 0
	v_add_u32_e32 v3, 0, v2
	ds_read_b128 v[18:21], v3 offset:2448
	ds_read_b128 v[28:31], v3 offset:2464
	ds_read_b128 v[36:39], v3 offset:2480
	v_fma_f32 v3, -v195, v22, v203
	v_fma_f32 v6, -v15, v24, 0
	v_fma_f32 v8, -v13, v25, 0
	s_waitcnt lgkmcnt(3)
	v_fma_f32 v3, -v11, v32, v3
	v_fma_f32 v5, -v9, v33, v5
	v_fma_f32 v6, -v7, v34, v6
	v_fma_f32 v8, -v35, v4, v8
	v_add_f32_e32 v3, v5, v3
	v_add_f32_e32 v5, v8, v6
	v_add_f32_e32 v5, v5, v3
	s_waitcnt lgkmcnt(2)
	v_fma_f32 v6, -v17, v19, 0
	v_add_u32_e32 v3, 0, v2
	ds_read_b128 v[22:25], v3 offset:2720
	ds_read_b128 v[32:35], v3 offset:2736
	s_waitcnt lgkmcnt(2)
	ds_read_b128 v[38:41], v3 offset:2752
	v_fma_f32 v3, -v195, v18, v204
	v_fma_f32 v8, -v15, v20, 0
	v_fma_f32 v10, -v13, v21, 0
	v_fma_f32 v3, -v11, v28, v3
	v_fma_f32 v6, -v9, v29, v6
	v_fma_f32 v8, -v7, v30, v8
	v_fma_f32 v10, -v4, v31, v10
	v_fma_f32 v3, -v36, v5, v3
	v_add_f32_e32 v3, v6, v3
	v_add_f32_e32 v6, v10, v8
	v_add_f32_e32 v6, v6, v3
	s_waitcnt lgkmcnt(2)
	v_fma_f32 v8, -v17, v23, 0
	v_add_u32_e32 v3, 0, v2
	ds_read_b128 v[18:21], v3 offset:2992
	ds_read_b128 v[28:31], v3 offset:3008
	s_waitcnt lgkmcnt(2)
	ds_read_b128 v[40:43], v3 offset:3024
	v_fma_f32 v3, -v195, v22, v205
	v_fma_f32 v10, -v15, v24, 0
	v_fma_f32 v12, -v13, v25, 0
	v_fma_f32 v3, -v11, v32, v3
	v_fma_f32 v8, -v9, v33, v8
	v_fma_f32 v10, -v7, v34, v10
	v_fma_f32 v12, -v4, v35, v12
	v_fma_f32 v3, -v5, v38, v3
	v_fma_f32 v8, -v39, v6, v8
	v_add_f32_e32 v3, v8, v3
	v_add_f32_e32 v8, v12, v10
	v_add_f32_e32 v8, v8, v3
	s_waitcnt lgkmcnt(2)
	v_fma_f32 v10, -v17, v19, 0
	v_add_u32_e32 v3, 0, v2
	ds_read_b128 v[22:25], v3 offset:3264
	ds_read_b128 v[32:35], v3 offset:3280
	ds_read_b128 v[36:39], v3 offset:3296
	v_fma_f32 v3, -v195, v18, v206
	v_fma_f32 v12, -v15, v20, 0
	v_fma_f32 v14, -v13, v21, 0
	s_waitcnt lgkmcnt(4)
	v_fma_f32 v3, -v11, v28, v3
	v_fma_f32 v10, -v9, v29, v10
	v_fma_f32 v12, -v7, v30, v12
	v_fma_f32 v14, -v4, v31, v14
	s_waitcnt lgkmcnt(3)
	v_fma_f32 v3, -v5, v40, v3
	v_fma_f32 v10, -v6, v41, v10
	v_fma_f32 v12, -v42, v8, v12
	v_add_f32_e32 v3, v10, v3
	v_add_f32_e32 v10, v14, v12
	v_add_f32_e32 v10, v10, v3
	s_waitcnt lgkmcnt(2)
	v_fma_f32 v12, -v17, v23, 0
	v_add_u32_e32 v3, 0, v2
	ds_read_b128 v[18:21], v3 offset:3536
	ds_read_b128 v[28:31], v3 offset:3552
	ds_read_b128 v[40:43], v3 offset:3568
	ds_read_b128 v[44:47], v3 offset:3584
	v_fma_f32 v3, -v195, v22, v207
	v_fma_f32 v14, -v15, v24, 0
	v_fma_f32 v16, -v13, v25, 0
	s_waitcnt lgkmcnt(5)
	v_fma_f32 v3, -v11, v32, v3
	v_fma_f32 v12, -v9, v33, v12
	v_fma_f32 v14, -v7, v34, v14
	v_fma_f32 v16, -v4, v35, v16
	s_waitcnt lgkmcnt(4)
	v_fma_f32 v3, -v5, v36, v3
	v_fma_f32 v12, -v6, v37, v12
	v_fma_f32 v14, -v8, v38, v14
	v_fma_f32 v16, -v39, v10, v16
	v_add_f32_e32 v3, v12, v3
	v_add_f32_e32 v12, v16, v14
	v_add_f32_e32 v12, v12, v3
	s_waitcnt lgkmcnt(3)
	v_fma_f32 v14, -v17, v19, 0
	v_add_u32_e32 v3, 0, v2
	ds_read_b128 v[22:25], v3 offset:3808
	ds_read_b128 v[32:35], v3 offset:3824
	ds_read_b128 v[36:39], v3 offset:3840
	s_waitcnt lgkmcnt(3)
	ds_read_b128 v[46:49], v3 offset:3856
	v_fma_f32 v3, -v195, v18, v208
	v_fma_f32 v16, -v15, v20, 0
	v_fma_f32 v18, -v13, v21, 0
	v_fma_f32 v3, -v11, v28, v3
	v_fma_f32 v14, -v9, v29, v14
	v_fma_f32 v16, -v7, v30, v16
	v_fma_f32 v18, -v4, v31, v18
	v_fma_f32 v3, -v5, v40, v3
	v_fma_f32 v14, -v6, v41, v14
	v_fma_f32 v16, -v8, v42, v16
	v_fma_f32 v18, -v10, v43, v18
	v_fma_f32 v3, -v44, v12, v3
	v_add_f32_e32 v3, v14, v3
	v_add_f32_e32 v14, v18, v16
	v_add_f32_e32 v14, v14, v3
	s_waitcnt lgkmcnt(3)
	v_fma_f32 v16, -v17, v23, 0
	v_add_u32_e32 v3, 0, v2
	ds_read_b128 v[18:21], v3 offset:4080
	ds_read_b128 v[28:31], v3 offset:4096
	ds_read_b128 v[40:43], v3 offset:4112
	s_waitcnt lgkmcnt(3)
	ds_read_b128 v[48:51], v3 offset:4128
	v_fma_f32 v3, -v195, v22, v209
	v_fma_f32 v22, -v15, v24, 0
	v_fma_f32 v23, -v13, v25, 0
	v_fma_f32 v3, -v11, v32, v3
	v_fma_f32 v16, -v9, v33, v16
	v_fma_f32 v22, -v7, v34, v22
	v_fma_f32 v23, -v4, v35, v23
	v_fma_f32 v3, -v5, v36, v3
	v_fma_f32 v16, -v6, v37, v16
	v_fma_f32 v22, -v8, v38, v22
	v_fma_f32 v23, -v10, v39, v23
	v_fma_f32 v3, -v12, v46, v3
	v_fma_f32 v16, -v47, v14, v16
	v_add_f32_e32 v3, v16, v3
	v_add_f32_e32 v16, v23, v22
	v_add_f32_e32 v16, v16, v3
	s_nop 0
	v_add_u32_e32 v3, 0, v2
	ds_read_b128 v[22:25], v3 offset:4352
	ds_read_b128 v[32:35], v3 offset:4368
	ds_read_b128 v[36:39], v3 offset:4384
	ds_read_b128 v[44:47], v3 offset:4400
	s_waitcnt lgkmcnt(7)
	v_fma_f32 v3, -v195, v18, v210
	v_fma_f32 v18, -v17, v19, 0
	v_fma_f32 v19, -v15, v20, 0
	v_fma_f32 v20, -v13, v21, 0
	s_waitcnt lgkmcnt(6)
	v_fma_f32 v3, -v11, v28, v3
	v_fma_f32 v18, -v9, v29, v18
	v_fma_f32 v19, -v7, v30, v19
	v_fma_f32 v20, -v4, v31, v20
	s_waitcnt lgkmcnt(5)
	v_fma_f32 v3, -v5, v40, v3
	v_fma_f32 v18, -v6, v41, v18
	v_fma_f32 v19, -v8, v42, v19
	v_fma_f32 v20, -v10, v43, v20
	s_waitcnt lgkmcnt(4)
	v_fma_f32 v3, -v12, v48, v3
	v_fma_f32 v18, -v14, v49, v18
	v_fma_f32 v19, -v50, v16, v19
	v_add_f32_e32 v3, v18, v3
	v_add_f32_e32 v18, v20, v19
	v_add_f32_e32 v18, v18, v3
	s_waitcnt lgkmcnt(3)
	v_fma_f32 v19, -v17, v23, 0
	v_add_u32_e32 v3, 0, v2
	ds_read_b128 v[28:31], v3 offset:4624
	ds_read_b128 v[40:43], v3 offset:4640
	ds_read_b128 v[48:51], v3 offset:4656
	ds_read_b128 v[52:55], v3 offset:4672
	ds_read_b128 v[56:59], v3 offset:4688
	v_fma_f32 v3, -v195, v22, v211
	v_fma_f32 v20, -v15, v24, 0
	v_fma_f32 v21, -v13, v25, 0
	s_waitcnt lgkmcnt(7)
	v_fma_f32 v3, -v11, v32, v3
	v_fma_f32 v19, -v9, v33, v19
	v_fma_f32 v20, -v7, v34, v20
	v_fma_f32 v21, -v4, v35, v21
	s_waitcnt lgkmcnt(6)
	v_fma_f32 v3, -v5, v36, v3
	v_fma_f32 v19, -v6, v37, v19
	v_fma_f32 v20, -v8, v38, v20
	v_fma_f32 v21, -v10, v39, v21
	s_waitcnt lgkmcnt(5)
	v_fma_f32 v3, -v12, v44, v3
	v_fma_f32 v19, -v14, v45, v19
	v_fma_f32 v20, -v16, v46, v20
	v_fma_f32 v21, -v47, v18, v21
	v_add_f32_e32 v3, v19, v3
	v_add_f32_e32 v19, v21, v20
	v_add_f32_e32 v19, v19, v3
	s_waitcnt lgkmcnt(4)
	v_fma_f32 v20, -v17, v29, 0
	v_add_u32_e32 v3, 0, v2
	ds_read_b128 v[22:25], v3 offset:4896
	ds_read_b128 v[32:35], v3 offset:4912
	ds_read_b128 v[36:39], v3 offset:4928
	ds_read_b128 v[44:47], v3 offset:4944
	s_waitcnt lgkmcnt(4)
	ds_read_b128 v[58:61], v3 offset:4960
	v_fma_f32 v3, -v195, v28, v212
	v_fma_f32 v21, -v15, v30, 0
	v_fma_f32 v27, -v13, v31, 0
	v_fma_f32 v3, -v11, v40, v3
	v_fma_f32 v20, -v9, v41, v20
	v_fma_f32 v21, -v7, v42, v21
	v_fma_f32 v27, -v4, v43, v27
	v_fma_f32 v3, -v5, v48, v3
	v_fma_f32 v20, -v6, v49, v20
	v_fma_f32 v21, -v8, v50, v21
	v_fma_f32 v27, -v10, v51, v27
	v_fma_f32 v3, -v12, v52, v3
	v_fma_f32 v20, -v14, v53, v20
	v_fma_f32 v21, -v16, v54, v21
	v_fma_f32 v27, -v18, v55, v27
	v_fma_f32 v3, -v56, v19, v3
	v_add_f32_e32 v3, v20, v3
	v_add_f32_e32 v20, v27, v21
	v_add_f32_e32 v20, v20, v3
	s_waitcnt lgkmcnt(4)
	v_fma_f32 v21, -v17, v23, 0
	v_add_u32_e32 v3, 0, v2
	ds_read_b128 v[28:31], v3 offset:5168
	ds_read_b128 v[40:43], v3 offset:5184
	ds_read_b128 v[48:51], v3 offset:5200
	ds_read_b128 v[52:55], v3 offset:5216
	s_waitcnt lgkmcnt(4)
	ds_read_b128 v[60:63], v3 offset:5232
	v_fma_f32 v3, -v195, v22, v213
	v_fma_f32 v22, -v15, v24, 0
	v_fma_f32 v23, -v13, v25, 0
	v_fma_f32 v3, -v11, v32, v3
	v_fma_f32 v21, -v9, v33, v21
	v_fma_f32 v22, -v7, v34, v22
	v_fma_f32 v23, -v4, v35, v23
	v_fma_f32 v3, -v5, v36, v3
	v_fma_f32 v21, -v6, v37, v21
	v_fma_f32 v22, -v8, v38, v22
	v_fma_f32 v23, -v10, v39, v23
	v_fma_f32 v3, -v12, v44, v3
	v_fma_f32 v21, -v14, v45, v21
	v_fma_f32 v22, -v16, v46, v22
	v_fma_f32 v23, -v18, v47, v23
	v_fma_f32 v3, -v19, v58, v3
	v_fma_f32 v21, -v59, v20, v21
	v_add_f32_e32 v3, v21, v3
	v_add_f32_e32 v21, v23, v22
	v_add_f32_e32 v21, v21, v3
	s_waitcnt lgkmcnt(4)
	v_fma_f32 v22, -v17, v29, 0
	v_add_u32_e32 v3, 0, v2
	ds_read_b128 v[32:35], v3 offset:5440
	ds_read_b128 v[36:39], v3 offset:5456
	ds_read_b128 v[44:47], v3 offset:5472
	ds_read_b128 v[56:59], v3 offset:5488
	ds_read_b128 v[64:67], v3 offset:5504
	v_fma_f32 v3, -v195, v28, v214
	v_fma_f32 v23, -v15, v30, 0
	v_fma_f32 v24, -v13, v31, 0
	s_waitcnt lgkmcnt(8)
	v_fma_f32 v3, -v11, v40, v3
	v_fma_f32 v22, -v9, v41, v22
	v_fma_f32 v23, -v7, v42, v23
	v_fma_f32 v24, -v4, v43, v24
	s_waitcnt lgkmcnt(7)
	v_fma_f32 v3, -v5, v48, v3
	v_fma_f32 v22, -v6, v49, v22
	v_fma_f32 v23, -v8, v50, v23
	v_fma_f32 v24, -v10, v51, v24
	s_waitcnt lgkmcnt(6)
	v_fma_f32 v3, -v12, v52, v3
	v_fma_f32 v22, -v14, v53, v22
	v_fma_f32 v23, -v16, v54, v23
	v_fma_f32 v24, -v18, v55, v24
	s_waitcnt lgkmcnt(5)
	v_fma_f32 v3, -v19, v60, v3
	v_fma_f32 v22, -v20, v61, v22
	v_fma_f32 v23, -v62, v21, v23
	v_add_f32_e32 v3, v22, v3
	v_add_f32_e32 v22, v24, v23
	v_add_f32_e32 v22, v22, v3
	s_waitcnt lgkmcnt(4)
	v_fma_f32 v23, -v17, v33, 0
	v_add_u32_e32 v3, 0, v2
	ds_read_b128 v[28:31], v3 offset:5712
	ds_read_b128 v[40:43], v3 offset:5728
	ds_read_b128 v[48:51], v3 offset:5744
	ds_read_b128 v[52:55], v3 offset:5760
	ds_read_b128 v[60:63], v3 offset:5776
	ds_read_b128 v[68:71], v3 offset:5792
	v_fma_f32 v3, -v195, v32, v215
	v_fma_f32 v24, -v15, v34, 0
	v_fma_f32 v25, -v13, v35, 0
	s_waitcnt lgkmcnt(9)
	v_fma_f32 v3, -v11, v36, v3
	v_fma_f32 v23, -v9, v37, v23
	v_fma_f32 v24, -v7, v38, v24
	v_fma_f32 v25, -v4, v39, v25
	s_waitcnt lgkmcnt(8)
	v_fma_f32 v3, -v5, v44, v3
	v_fma_f32 v23, -v6, v45, v23
	v_fma_f32 v24, -v8, v46, v24
	v_fma_f32 v25, -v10, v47, v25
	s_waitcnt lgkmcnt(7)
	v_fma_f32 v3, -v12, v56, v3
	v_fma_f32 v23, -v14, v57, v23
	v_fma_f32 v24, -v16, v58, v24
	v_fma_f32 v25, -v18, v59, v25
	s_waitcnt lgkmcnt(6)
	v_fma_f32 v3, -v19, v64, v3
	v_fma_f32 v23, -v20, v65, v23
	v_fma_f32 v24, -v21, v66, v24
	v_fma_f32 v25, -v67, v22, v25
	v_add_f32_e32 v3, v23, v3
	v_add_f32_e32 v23, v25, v24
	v_add_f32_e32 v23, v23, v3
	s_waitcnt lgkmcnt(5)
	v_fma_f32 v24, -v17, v29, 0
	v_add_u32_e32 v3, 0, v2
	ds_read_b128 v[32:35], v3 offset:5984
	ds_read_b128 v[36:39], v3 offset:6000
	ds_read_b128 v[44:47], v3 offset:6016
	ds_read_b128 v[56:59], v3 offset:6032
	ds_read_b128 v[64:67], v3 offset:6048
	s_waitcnt lgkmcnt(5)
	ds_read_b128 v[70:73], v3 offset:6064
	v_fma_f32 v3, -v195, v28, v216
	v_fma_f32 v25, -v15, v30, 0
	v_fma_f32 v27, -v13, v31, 0
	v_fma_f32 v3, -v11, v40, v3
	v_fma_f32 v24, -v9, v41, v24
	v_fma_f32 v25, -v7, v42, v25
	v_fma_f32 v27, -v4, v43, v27
	v_fma_f32 v3, -v5, v48, v3
	v_fma_f32 v24, -v6, v49, v24
	v_fma_f32 v25, -v8, v50, v25
	v_fma_f32 v27, -v10, v51, v27
	v_fma_f32 v3, -v12, v52, v3
	v_fma_f32 v24, -v14, v53, v24
	v_fma_f32 v25, -v16, v54, v25
	v_fma_f32 v27, -v18, v55, v27
	v_fma_f32 v3, -v19, v60, v3
	v_fma_f32 v24, -v20, v61, v24
	v_fma_f32 v25, -v21, v62, v25
	v_fma_f32 v27, -v22, v63, v27
	v_fma_f32 v3, -v68, v23, v3
	v_add_f32_e32 v3, v24, v3
	v_add_f32_e32 v24, v27, v25
	v_add_f32_e32 v24, v24, v3
	s_waitcnt lgkmcnt(5)
	v_fma_f32 v25, -v17, v33, 0
	v_add_u32_e32 v3, 0, v2
	ds_read_b128 v[28:31], v3 offset:6256
	ds_read_b128 v[40:43], v3 offset:6272
	ds_read_b128 v[48:51], v3 offset:6288
	ds_read_b128 v[52:55], v3 offset:6304
	ds_read_b128 v[60:63], v3 offset:6320
	s_waitcnt lgkmcnt(5)
	ds_read_b128 v[72:75], v3 offset:6336
	v_fma_f32 v3, -v195, v32, v217
	v_fma_f32 v27, -v15, v34, 0
	v_fma_f32 v32, -v13, v35, 0
	v_fma_f32 v3, -v11, v36, v3
	v_fma_f32 v25, -v9, v37, v25
	v_fma_f32 v27, -v7, v38, v27
	v_fma_f32 v32, -v4, v39, v32
	v_fma_f32 v3, -v5, v44, v3
	v_fma_f32 v25, -v6, v45, v25
	v_fma_f32 v27, -v8, v46, v27
	v_fma_f32 v32, -v10, v47, v32
	v_fma_f32 v3, -v12, v56, v3
	v_fma_f32 v25, -v14, v57, v25
	v_fma_f32 v27, -v16, v58, v27
	v_fma_f32 v32, -v18, v59, v32
	v_fma_f32 v3, -v19, v64, v3
	v_fma_f32 v25, -v20, v65, v25
	v_fma_f32 v27, -v21, v66, v27
	v_fma_f32 v32, -v22, v67, v32
	v_fma_f32 v3, -v23, v70, v3
	v_fma_f32 v25, -v71, v24, v25
	v_add_f32_e32 v3, v25, v3
	v_add_f32_e32 v25, v32, v27
	v_add_f32_e32 v25, v25, v3
	s_waitcnt lgkmcnt(5)
	v_fma_f32 v27, -v17, v29, 0
	v_add_u32_e32 v3, 0, v2
	ds_read_b128 v[32:35], v3 offset:6528
	ds_read_b128 v[36:39], v3 offset:6544
	ds_read_b128 v[44:47], v3 offset:6560
	ds_read_b128 v[56:59], v3 offset:6576
	ds_read_b128 v[64:67], v3 offset:6592
	ds_read_b128 v[68:71], v3 offset:6608
	v_fma_f32 v3, -v195, v28, v218
	v_fma_f32 v28, -v15, v30, 0
	v_fma_f32 v29, -v13, v31, 0
	s_waitcnt lgkmcnt(10)
	v_fma_f32 v3, -v11, v40, v3
	v_fma_f32 v27, -v9, v41, v27
	v_fma_f32 v28, -v7, v42, v28
	v_fma_f32 v29, -v4, v43, v29
	s_waitcnt lgkmcnt(9)
	v_fma_f32 v3, -v5, v48, v3
	v_fma_f32 v27, -v6, v49, v27
	v_fma_f32 v28, -v8, v50, v28
	v_fma_f32 v29, -v10, v51, v29
	s_waitcnt lgkmcnt(8)
	v_fma_f32 v3, -v12, v52, v3
	v_fma_f32 v27, -v14, v53, v27
	v_fma_f32 v28, -v16, v54, v28
	v_fma_f32 v29, -v18, v55, v29
	s_waitcnt lgkmcnt(7)
	v_fma_f32 v3, -v19, v60, v3
	v_fma_f32 v27, -v20, v61, v27
	v_fma_f32 v28, -v21, v62, v28
	v_fma_f32 v29, -v22, v63, v29
	s_waitcnt lgkmcnt(6)
	v_fma_f32 v3, -v23, v72, v3
	v_fma_f32 v27, -v24, v73, v27
	v_fma_f32 v28, -v74, v25, v28
	v_add_f32_e32 v3, v27, v3
	v_add_f32_e32 v27, v29, v28
	v_add_f32_e32 v27, v27, v3
	s_waitcnt lgkmcnt(5)
	v_fma_f32 v28, -v17, v33, 0
	v_add_u32_e32 v3, 0, v2
	ds_read_b128 v[40:43], v3 offset:6800
	ds_read_b128 v[48:51], v3 offset:6816
	ds_read_b128 v[52:55], v3 offset:6832
	ds_read_b128 v[60:63], v3 offset:6848
	ds_read_b128 v[72:75], v3 offset:6864
	ds_read_b128 v[76:79], v3 offset:6880
	ds_read_b128 v[140:143], v3 offset:6896
	v_fma_f32 v3, -v195, v32, v219
	v_fma_f32 v29, -v15, v34, 0
	v_fma_f32 v30, -v13, v35, 0
	s_waitcnt lgkmcnt(11)
	v_fma_f32 v3, -v11, v36, v3
	v_fma_f32 v28, -v9, v37, v28
	v_fma_f32 v29, -v7, v38, v29
	v_fma_f32 v30, -v4, v39, v30
	s_waitcnt lgkmcnt(10)
	v_fma_f32 v3, -v5, v44, v3
	v_fma_f32 v28, -v6, v45, v28
	v_fma_f32 v29, -v8, v46, v29
	v_fma_f32 v30, -v10, v47, v30
	s_waitcnt lgkmcnt(9)
	v_fma_f32 v3, -v12, v56, v3
	v_fma_f32 v28, -v14, v57, v28
	v_fma_f32 v29, -v16, v58, v29
	v_fma_f32 v30, -v18, v59, v30
	s_waitcnt lgkmcnt(8)
	v_fma_f32 v3, -v19, v64, v3
	v_fma_f32 v28, -v20, v65, v28
	v_fma_f32 v29, -v21, v66, v29
	v_fma_f32 v30, -v22, v67, v30
	s_waitcnt lgkmcnt(7)
	v_fma_f32 v3, -v23, v68, v3
	v_fma_f32 v28, -v24, v69, v28
	v_fma_f32 v29, -v25, v70, v29
	v_fma_f32 v30, -v71, v27, v30
	v_add_f32_e32 v3, v28, v3
	v_add_f32_e32 v28, v30, v29
	v_add_f32_e32 v28, v28, v3
	s_waitcnt lgkmcnt(6)
	v_fma_f32 v29, -v17, v41, 0
	v_add_u32_e32 v3, 0, v2
	ds_read_b128 v[30:33], v3 offset:7072
	ds_read_b128 v[34:37], v3 offset:7088
	ds_read_b128 v[44:47], v3 offset:7104
	ds_read_b128 v[56:59], v3 offset:7120
	ds_read_b128 v[64:67], v3 offset:7136
	ds_read_b128 v[68:71], v3 offset:7152
	s_waitcnt lgkmcnt(6)
	ds_read_b128 v[142:145], v3 offset:7168
	v_fma_f32 v3, -v195, v40, v220
	v_fma_f32 v38, -v15, v42, 0
	v_fma_f32 v39, -v13, v43, 0
	v_fma_f32 v3, -v11, v48, v3
	v_fma_f32 v29, -v9, v49, v29
	v_fma_f32 v38, -v7, v50, v38
	v_fma_f32 v39, -v4, v51, v39
	v_fma_f32 v3, -v5, v52, v3
	v_fma_f32 v29, -v6, v53, v29
	v_fma_f32 v38, -v8, v54, v38
	v_fma_f32 v39, -v10, v55, v39
	v_fma_f32 v3, -v12, v60, v3
	v_fma_f32 v29, -v14, v61, v29
	v_fma_f32 v38, -v16, v62, v38
	v_fma_f32 v39, -v18, v63, v39
	v_fma_f32 v3, -v19, v72, v3
	v_fma_f32 v29, -v20, v73, v29
	v_fma_f32 v38, -v21, v74, v38
	v_fma_f32 v39, -v22, v75, v39
	v_fma_f32 v3, -v23, v76, v3
	v_fma_f32 v29, -v24, v77, v29
	v_fma_f32 v38, -v25, v78, v38
	v_fma_f32 v39, -v27, v79, v39
	v_fma_f32 v3, -v140, v28, v3
	v_add_f32_e32 v3, v29, v3
	v_add_f32_e32 v29, v39, v38
	v_add_f32_e32 v29, v29, v3
	s_nop 0
	v_add_u32_e32 v3, 0, v2
	ds_read_b128 v[38:41], v3 offset:7344
	ds_read_b128 v[48:51], v3 offset:7360
	ds_read_b128 v[52:55], v3 offset:7376
	ds_read_b128 v[60:63], v3 offset:7392
	ds_read_b128 v[72:75], v3 offset:7408
	ds_read_b128 v[76:79], v3 offset:7424
	s_waitcnt lgkmcnt(6)
	ds_read_b128 v[144:147], v3 offset:7440
	v_fma_f32 v3, -v195, v30, v221
	v_fma_f32 v30, -v17, v31, 0
	v_fma_f32 v31, -v15, v32, 0
	v_fma_f32 v32, -v13, v33, 0
	v_fma_f32 v3, -v11, v34, v3
	v_fma_f32 v30, -v9, v35, v30
	v_fma_f32 v31, -v7, v36, v31
	v_fma_f32 v32, -v4, v37, v32
	v_fma_f32 v3, -v5, v44, v3
	v_fma_f32 v30, -v6, v45, v30
	v_fma_f32 v31, -v8, v46, v31
	v_fma_f32 v32, -v10, v47, v32
	v_fma_f32 v3, -v12, v56, v3
	v_fma_f32 v30, -v14, v57, v30
	v_fma_f32 v31, -v16, v58, v31
	v_fma_f32 v32, -v18, v59, v32
	v_fma_f32 v3, -v19, v64, v3
	v_fma_f32 v30, -v20, v65, v30
	v_fma_f32 v31, -v21, v66, v31
	v_fma_f32 v32, -v22, v67, v32
	v_fma_f32 v3, -v23, v68, v3
	v_fma_f32 v30, -v24, v69, v30
	v_fma_f32 v31, -v25, v70, v31
	v_fma_f32 v32, -v27, v71, v32
	v_fma_f32 v3, -v28, v142, v3
	v_fma_f32 v30, -v143, v29, v30
	v_add_f32_e32 v3, v30, v3
	v_add_f32_e32 v30, v32, v31
	v_add_f32_e32 v30, v30, v3
	s_waitcnt lgkmcnt(6)
	v_fma_f32 v31, -v17, v39, 0
	v_add_u32_e32 v3, 0, v2
	ds_read_b128 v[32:35], v3 offset:7616
	ds_read_b128 v[42:45], v3 offset:7632
	ds_read_b128 v[56:59], v3 offset:7648
	ds_read_b128 v[64:67], v3 offset:7664
	ds_read_b128 v[68:71], v3 offset:7680
	ds_read_b128 v[140:143], v3 offset:7696
	ds_read_b128 v[148:151], v3 offset:7712
	v_fma_f32 v3, -v195, v38, v222
	v_fma_f32 v36, -v15, v40, 0
	v_fma_f32 v37, -v13, v41, 0
	s_waitcnt lgkmcnt(12)
	v_fma_f32 v3, -v11, v48, v3
	v_fma_f32 v31, -v9, v49, v31
	v_fma_f32 v36, -v7, v50, v36
	v_fma_f32 v37, -v4, v51, v37
	s_waitcnt lgkmcnt(11)
	v_fma_f32 v3, -v5, v52, v3
	v_fma_f32 v31, -v6, v53, v31
	v_fma_f32 v36, -v8, v54, v36
	v_fma_f32 v37, -v10, v55, v37
	s_waitcnt lgkmcnt(10)
	v_fma_f32 v3, -v12, v60, v3
	v_fma_f32 v31, -v14, v61, v31
	v_fma_f32 v36, -v16, v62, v36
	v_fma_f32 v37, -v18, v63, v37
	s_waitcnt lgkmcnt(9)
	v_fma_f32 v3, -v19, v72, v3
	v_fma_f32 v31, -v20, v73, v31
	v_fma_f32 v36, -v21, v74, v36
	v_fma_f32 v37, -v22, v75, v37
	s_waitcnt lgkmcnt(8)
	v_fma_f32 v3, -v23, v76, v3
	v_fma_f32 v31, -v24, v77, v31
	v_fma_f32 v36, -v25, v78, v36
	v_fma_f32 v37, -v27, v79, v37
	s_waitcnt lgkmcnt(7)
	v_fma_f32 v3, -v28, v144, v3
	v_fma_f32 v31, -v29, v145, v31
	v_fma_f32 v36, -v146, v30, v36
	v_add_f32_e32 v3, v31, v3
	v_add_f32_e32 v31, v37, v36
	v_add_f32_e32 v31, v31, v3
	s_nop 0
	v_add_u32_e32 v3, 0, v2
	ds_read_b128 v[36:39], v3 offset:7888
	ds_read_b128 v[46:49], v3 offset:7904
	ds_read_b128 v[50:53], v3 offset:7920
	ds_read_b128 v[60:63], v3 offset:7936
	ds_read_b128 v[72:75], v3 offset:7952
	ds_read_b128 v[76:79], v3 offset:7968
	ds_read_b128 v[144:147], v3 offset:7984
	ds_read_b128 v[152:155], v3 offset:8000
	s_waitcnt lgkmcnt(14)
	v_fma_f32 v3, -v195, v32, v223
	v_fma_f32 v32, -v17, v33, 0
	v_fma_f32 v33, -v15, v34, 0
	v_fma_f32 v34, -v13, v35, 0
	s_waitcnt lgkmcnt(13)
	v_fma_f32 v3, -v11, v42, v3
	v_fma_f32 v32, -v9, v43, v32
	v_fma_f32 v33, -v7, v44, v33
	v_fma_f32 v34, -v4, v45, v34
	s_waitcnt lgkmcnt(12)
	v_fma_f32 v3, -v5, v56, v3
	v_fma_f32 v32, -v6, v57, v32
	v_fma_f32 v33, -v8, v58, v33
	v_fma_f32 v34, -v10, v59, v34
	s_waitcnt lgkmcnt(11)
	v_fma_f32 v3, -v12, v64, v3
	v_fma_f32 v32, -v14, v65, v32
	v_fma_f32 v33, -v16, v66, v33
	v_fma_f32 v34, -v18, v67, v34
	s_waitcnt lgkmcnt(10)
	v_fma_f32 v3, -v19, v68, v3
	v_fma_f32 v32, -v20, v69, v32
	v_fma_f32 v33, -v21, v70, v33
	v_fma_f32 v34, -v22, v71, v34
	s_waitcnt lgkmcnt(9)
	v_fma_f32 v3, -v23, v140, v3
	v_fma_f32 v32, -v24, v141, v32
	v_fma_f32 v33, -v25, v142, v33
	v_fma_f32 v34, -v27, v143, v34
	s_waitcnt lgkmcnt(8)
	v_fma_f32 v3, -v28, v148, v3
	v_fma_f32 v32, -v29, v149, v32
	v_fma_f32 v33, -v30, v150, v33
	v_fma_f32 v34, -v151, v31, v34
	v_add_f32_e32 v3, v32, v3
	v_add_f32_e32 v32, v34, v33
	v_add_f32_e32 v32, v32, v3
	s_waitcnt lgkmcnt(7)
	v_fma_f32 v33, -v17, v37, 0
	v_add_u32_e32 v3, 0, v2
	ds_read_b128 v[40:43], v3 offset:8160
	ds_read_b128 v[54:57], v3 offset:8176
	ds_read_b128 v[64:67], v3 offset:8192
	ds_read_b128 v[68:71], v3 offset:8208
	ds_read_b128 v[140:143], v3 offset:8224
	ds_read_b128 v[148:151], v3 offset:8240
	s_waitcnt lgkmcnt(6)
	ds_read_b128 v[154:157], v3 offset:8256
	ds_read_b128 v[158:161], v3 offset:8272
	v_fma_f32 v3, -v195, v36, v224
	v_fma_f32 v34, -v15, v38, 0
	v_fma_f32 v35, -v13, v39, 0
	v_fma_f32 v3, -v11, v46, v3
	v_fma_f32 v33, -v9, v47, v33
	v_fma_f32 v34, -v7, v48, v34
	v_fma_f32 v35, -v4, v49, v35
	v_fma_f32 v3, -v5, v50, v3
	v_fma_f32 v33, -v6, v51, v33
	v_fma_f32 v34, -v8, v52, v34
	v_fma_f32 v35, -v10, v53, v35
	v_fma_f32 v3, -v12, v60, v3
	v_fma_f32 v33, -v14, v61, v33
	v_fma_f32 v34, -v16, v62, v34
	v_fma_f32 v35, -v18, v63, v35
	v_fma_f32 v3, -v19, v72, v3
	v_fma_f32 v33, -v20, v73, v33
	v_fma_f32 v34, -v21, v74, v34
	v_fma_f32 v35, -v22, v75, v35
	v_fma_f32 v3, -v23, v76, v3
	v_fma_f32 v33, -v24, v77, v33
	v_fma_f32 v34, -v25, v78, v34
	v_fma_f32 v35, -v27, v79, v35
	v_fma_f32 v3, -v28, v144, v3
	v_fma_f32 v33, -v29, v145, v33
	v_fma_f32 v34, -v30, v146, v34
	v_fma_f32 v35, -v31, v147, v35
	v_fma_f32 v3, -v152, v32, v3
	v_add_f32_e32 v3, v33, v3
	v_add_f32_e32 v33, v35, v34
	v_add_f32_e32 v33, v33, v3
	s_waitcnt lgkmcnt(7)
	v_fma_f32 v34, -v17, v41, 0
	v_add_u32_e32 v3, 0, v2
	ds_read_b128 v[36:39], v3 offset:8432
	ds_read_b128 v[44:47], v3 offset:8448
	ds_read_b128 v[48:51], v3 offset:8464
	ds_read_b128 v[58:61], v3 offset:8480
	ds_read_b128 v[72:75], v3 offset:8496
	ds_read_b128 v[76:79], v3 offset:8512
	ds_read_b128 v[144:147], v3 offset:8528
	s_waitcnt lgkmcnt(7)
	ds_read_b128 v[160:163], v3 offset:8544
	v_fma_f32 v3, -v195, v40, v225
	v_fma_f32 v35, -v15, v42, 0
	v_fma_f32 v40, -v13, v43, 0
	v_fma_f32 v3, -v11, v54, v3
	v_fma_f32 v34, -v9, v55, v34
	v_fma_f32 v35, -v7, v56, v35
	v_fma_f32 v40, -v4, v57, v40
	v_fma_f32 v3, -v5, v64, v3
	v_fma_f32 v34, -v6, v65, v34
	v_fma_f32 v35, -v8, v66, v35
	v_fma_f32 v40, -v10, v67, v40
	v_fma_f32 v3, -v12, v68, v3
	v_fma_f32 v34, -v14, v69, v34
	v_fma_f32 v35, -v16, v70, v35
	v_fma_f32 v40, -v18, v71, v40
	v_fma_f32 v3, -v19, v140, v3
	v_fma_f32 v34, -v20, v141, v34
	v_fma_f32 v35, -v21, v142, v35
	v_fma_f32 v40, -v22, v143, v40
	v_fma_f32 v3, -v23, v148, v3
	v_fma_f32 v34, -v24, v149, v34
	v_fma_f32 v35, -v25, v150, v35
	v_fma_f32 v40, -v27, v151, v40
	v_fma_f32 v3, -v28, v154, v3
	v_fma_f32 v34, -v29, v155, v34
	v_fma_f32 v35, -v30, v156, v35
	v_fma_f32 v40, -v31, v157, v40
	v_fma_f32 v3, -v32, v158, v3
	v_fma_f32 v34, -v159, v33, v34
	v_add_f32_e32 v3, v34, v3
	v_add_f32_e32 v34, v40, v35
	v_add_f32_e32 v34, v34, v3
	s_waitcnt lgkmcnt(7)
	v_fma_f32 v3, -v17, v37, 0
	v_fma_f32 v2, -v195, v36, v226
	v_fma_f32 v35, -v15, v38, 0
	v_fma_f32 v36, -v13, v39, 0
	s_waitcnt lgkmcnt(6)
	v_fma_f32 v2, -v11, v44, v2
	v_fma_f32 v3, -v9, v45, v3
	v_fma_f32 v35, -v7, v46, v35
	v_fma_f32 v36, -v4, v47, v36
	s_waitcnt lgkmcnt(5)
	v_fma_f32 v2, -v5, v48, v2
	v_fma_f32 v3, -v6, v49, v3
	v_fma_f32 v35, -v8, v50, v35
	v_fma_f32 v36, -v10, v51, v36
	s_waitcnt lgkmcnt(4)
	v_fma_f32 v2, -v12, v58, v2
	v_fma_f32 v3, -v14, v59, v3
	v_fma_f32 v35, -v16, v60, v35
	v_fma_f32 v36, -v18, v61, v36
	s_waitcnt lgkmcnt(3)
	v_fma_f32 v2, -v19, v72, v2
	v_fma_f32 v3, -v20, v73, v3
	v_fma_f32 v35, -v21, v74, v35
	v_fma_f32 v36, -v22, v75, v36
	s_waitcnt lgkmcnt(2)
	v_fma_f32 v2, -v23, v76, v2
	v_fma_f32 v3, -v24, v77, v3
	v_fma_f32 v35, -v25, v78, v35
	v_fma_f32 v36, -v27, v79, v36
	s_waitcnt lgkmcnt(1)
	v_fma_f32 v2, -v28, v144, v2
	v_fma_f32 v3, -v29, v145, v3
	v_fma_f32 v35, -v30, v146, v35
	v_fma_f32 v36, -v31, v147, v36
	s_waitcnt lgkmcnt(0)
	v_fma_f32 v2, -v32, v160, v2
	v_fma_f32 v3, -v33, v161, v3
	v_fma_f32 v35, -v162, v34, v35
	v_add_f32_e32 v2, v3, v2
	v_add_f32_e32 v3, v36, v35
	v_add_f32_e32 v35, v3, v2
	ds_read2st64_b32 v[2:3], v186 offset1:2
	s_waitcnt lgkmcnt(0)
	v_mul_f32_e32 v36, v2, v3
	v_mul_f32_e32 v3, v195, v2
	v_cvt_pk_bf16_f32 v3, v3, v3
	ds_write_b16 v190, v3
	v_mul_f32_e32 v3, v195, v36
	v_cvt_pk_bf16_f32 v3, v3, v3
	ds_write_b16 v190, v3 offset:64
	v_add_u32_e32 v3, v171, v189
	s_and_saveexec_b64 s[18:19], s[8:9]
	ds_write_b16 v3, v227 offset:128
	s_or_b64 exec, exec, s[18:19]
	v_mul_f32_e32 v37, v17, v2
	v_cvt_pk_bf16_f32 v37, v37, v37
	ds_write_b16 v190, v37 offset:272
	v_mul_f32_e32 v37, v17, v36
	v_bfe_u32 v38, v37, 16, 1
	v_add3_u32 v37, v37, v38, s54
	ds_write_b16_d16_hi v190, v37 offset:336
	s_and_saveexec_b64 s[18:19], s[8:9]
	v_cvt_pk_bf16_f32 v17, -v17, -v17
	ds_write_b16 v3, v17 offset:400
	s_or_b64 exec, exec, s[18:19]
	v_mul_f32_e32 v17, v15, v2
	v_cvt_pk_bf16_f32 v17, v17, v17
	ds_write_b16 v190, v17 offset:544
	v_mul_f32_e32 v17, v15, v36
	v_bfe_u32 v37, v17, 16, 1
	v_add3_u32 v17, v17, v37, s54
	ds_write_b16_d16_hi v190, v17 offset:608
	s_and_saveexec_b64 s[18:19], s[8:9]
	v_cvt_pk_bf16_f32 v15, -v15, -v15
	ds_write_b16 v3, v15 offset:672
	s_or_b64 exec, exec, s[18:19]
	v_mul_f32_e32 v15, v13, v2
	v_cvt_pk_bf16_f32 v15, v15, v15
	ds_write_b16 v190, v15 offset:816
	v_mul_f32_e32 v15, v13, v36
	v_bfe_u32 v17, v15, 16, 1
	v_add3_u32 v15, v15, v17, s54
	ds_write_b16_d16_hi v190, v15 offset:880
	s_and_saveexec_b64 s[18:19], s[8:9]
	v_cvt_pk_bf16_f32 v13, -v13, -v13
	ds_write_b16 v3, v13 offset:944
	s_or_b64 exec, exec, s[18:19]
	v_mul_f32_e32 v13, v11, v2
	v_cvt_pk_bf16_f32 v13, v13, v13
	ds_write_b16 v190, v13 offset:1088
	v_mul_f32_e32 v13, v11, v36
	v_bfe_u32 v15, v13, 16, 1
	v_add3_u32 v13, v13, v15, s54
	ds_write_b16_d16_hi v190, v13 offset:1152
	s_and_saveexec_b64 s[18:19], s[8:9]
	v_cvt_pk_bf16_f32 v11, -v11, -v11
	ds_write_b16 v3, v11 offset:1216
	s_or_b64 exec, exec, s[18:19]
	v_mul_f32_e32 v11, v9, v2
	v_cvt_pk_bf16_f32 v11, v11, v11
	ds_write_b16 v190, v11 offset:1360
	v_mul_f32_e32 v11, v9, v36
	v_bfe_u32 v13, v11, 16, 1
	v_add3_u32 v11, v11, v13, s54
	ds_write_b16_d16_hi v190, v11 offset:1424
	s_and_saveexec_b64 s[18:19], s[8:9]
	v_cvt_pk_bf16_f32 v9, -v9, -v9
	ds_write_b16 v3, v9 offset:1488
	s_or_b64 exec, exec, s[18:19]
	v_mul_f32_e32 v9, v7, v2
	v_cvt_pk_bf16_f32 v9, v9, v9
	ds_write_b16 v190, v9 offset:1632
	v_mul_f32_e32 v9, v7, v36
	v_bfe_u32 v11, v9, 16, 1
	v_add3_u32 v9, v9, v11, s54
	ds_write_b16_d16_hi v190, v9 offset:1696
	s_and_saveexec_b64 s[18:19], s[8:9]
	v_cvt_pk_bf16_f32 v7, -v7, -v7
	ds_write_b16 v3, v7 offset:1760
	s_or_b64 exec, exec, s[18:19]
	v_mul_f32_e32 v7, v4, v2
	v_cvt_pk_bf16_f32 v7, v7, v7
	ds_write_b16 v190, v7 offset:1904
	v_mul_f32_e32 v7, v4, v36
	v_bfe_u32 v9, v7, 16, 1
	v_add3_u32 v7, v7, v9, s54
	ds_write_b16_d16_hi v190, v7 offset:1968
	s_and_saveexec_b64 s[18:19], s[8:9]
	v_cvt_pk_bf16_f32 v4, -v4, -v4
	ds_write_b16 v3, v4 offset:2032
	s_or_b64 exec, exec, s[18:19]
	v_mul_f32_e32 v4, v5, v2
	v_cvt_pk_bf16_f32 v4, v4, v4
	ds_write_b16 v190, v4 offset:2176
	v_mul_f32_e32 v4, v5, v36
	v_bfe_u32 v7, v4, 16, 1
	v_add3_u32 v4, v4, v7, s54
	ds_write_b16_d16_hi v190, v4 offset:2240
	s_and_saveexec_b64 s[18:19], s[8:9]
	v_cvt_pk_bf16_f32 v4, -v5, -v5
	ds_write_b16 v3, v4 offset:2304
	s_or_b64 exec, exec, s[18:19]
	v_mul_f32_e32 v4, v6, v2
	v_cvt_pk_bf16_f32 v4, v4, v4
	ds_write_b16 v190, v4 offset:2448
	v_mul_f32_e32 v4, v6, v36
	v_cvt_pk_bf16_f32 v4, v4, v4
	ds_write_b16 v190, v4 offset:2512
	s_and_saveexec_b64 s[18:19], s[8:9]
	v_cvt_pk_bf16_f32 v4, -v6, -v6
	ds_write_b16 v3, v4 offset:2576
	s_or_b64 exec, exec, s[18:19]
	v_mul_f32_e32 v4, v8, v2
	v_cvt_pk_bf16_f32 v4, v4, v4
	ds_write_b16 v190, v4 offset:2720
	v_mul_f32_e32 v4, v8, v36
	v_cvt_pk_bf16_f32 v4, v4, v4
	ds_write_b16 v190, v4 offset:2784
	s_and_saveexec_b64 s[18:19], s[8:9]
	v_cvt_pk_bf16_f32 v4, -v8, -v8
	ds_write_b16 v3, v4 offset:2848
	s_or_b64 exec, exec, s[18:19]
	v_mul_f32_e32 v4, v10, v2
	v_cvt_pk_bf16_f32 v4, v4, v4
	ds_write_b16 v190, v4 offset:2992
	v_mul_f32_e32 v4, v10, v36
	v_cvt_pk_bf16_f32 v4, v4, v4
	ds_write_b16 v190, v4 offset:3056
	s_and_saveexec_b64 s[18:19], s[8:9]
	v_cvt_pk_bf16_f32 v4, -v10, -v10
	ds_write_b16 v3, v4 offset:3120
	s_or_b64 exec, exec, s[18:19]
	v_mul_f32_e32 v4, v12, v2
	v_cvt_pk_bf16_f32 v4, v4, v4
	ds_write_b16 v190, v4 offset:3264
	v_mul_f32_e32 v4, v12, v36
	v_cvt_pk_bf16_f32 v4, v4, v4
	ds_write_b16 v190, v4 offset:3328
	s_and_saveexec_b64 s[18:19], s[8:9]
	v_cvt_pk_bf16_f32 v4, -v12, -v12
	ds_write_b16 v3, v4 offset:3392
	s_or_b64 exec, exec, s[18:19]
	v_mul_f32_e32 v4, v14, v2
	v_cvt_pk_bf16_f32 v4, v4, v4
	ds_write_b16 v190, v4 offset:3536
	v_mul_f32_e32 v4, v14, v36
	v_cvt_pk_bf16_f32 v4, v4, v4
	ds_write_b16 v190, v4 offset:3600
	s_and_saveexec_b64 s[18:19], s[8:9]
	v_cvt_pk_bf16_f32 v4, -v14, -v14
	ds_write_b16 v3, v4 offset:3664
	s_or_b64 exec, exec, s[18:19]
	v_mul_f32_e32 v4, v16, v2
	v_cvt_pk_bf16_f32 v4, v4, v4
	ds_write_b16 v190, v4 offset:3808
	v_mul_f32_e32 v4, v16, v36
	v_cvt_pk_bf16_f32 v4, v4, v4
	ds_write_b16 v190, v4 offset:3872
	s_and_saveexec_b64 s[18:19], s[8:9]
	v_cvt_pk_bf16_f32 v4, -v16, -v16
	ds_write_b16 v3, v4 offset:3936
	s_or_b64 exec, exec, s[18:19]
	v_mul_f32_e32 v4, v18, v2
	v_cvt_pk_bf16_f32 v4, v4, v4
	ds_write_b16 v190, v4 offset:4080
	v_mul_f32_e32 v4, v18, v36
	v_cvt_pk_bf16_f32 v4, v4, v4
	ds_write_b16 v190, v4 offset:4144
	s_and_saveexec_b64 s[18:19], s[8:9]
	v_cvt_pk_bf16_f32 v4, -v18, -v18
	ds_write_b16 v3, v4 offset:4208
	s_or_b64 exec, exec, s[18:19]
	v_mul_f32_e32 v4, v19, v2
	v_cvt_pk_bf16_f32 v4, v4, v4
	ds_write_b16 v190, v4 offset:4352
	v_mul_f32_e32 v4, v19, v36
	v_cvt_pk_bf16_f32 v4, v4, v4
	ds_write_b16 v190, v4 offset:4416
	s_and_saveexec_b64 s[18:19], s[8:9]
	v_cvt_pk_bf16_f32 v4, -v19, -v19
	ds_write_b16 v3, v4 offset:4480
	s_or_b64 exec, exec, s[18:19]
	v_mul_f32_e32 v4, v20, v2
	v_cvt_pk_bf16_f32 v4, v4, v4
	ds_write_b16 v190, v4 offset:4624
	v_mul_f32_e32 v4, v20, v36
	v_cvt_pk_bf16_f32 v4, v4, v4
	ds_write_b16 v190, v4 offset:4688
	s_and_saveexec_b64 s[18:19], s[8:9]
	v_cvt_pk_bf16_f32 v4, -v20, -v20
	ds_write_b16 v3, v4 offset:4752
	s_or_b64 exec, exec, s[18:19]
	v_mul_f32_e32 v4, v21, v2
	v_cvt_pk_bf16_f32 v4, v4, v4
	ds_write_b16 v190, v4 offset:4896
	v_mul_f32_e32 v4, v21, v36
	v_cvt_pk_bf16_f32 v4, v4, v4
	ds_write_b16 v190, v4 offset:4960
	s_and_saveexec_b64 s[18:19], s[8:9]
	v_cvt_pk_bf16_f32 v4, -v21, -v21
	ds_write_b16 v3, v4 offset:5024
	s_or_b64 exec, exec, s[18:19]
	v_mul_f32_e32 v4, v22, v2
	v_cvt_pk_bf16_f32 v4, v4, v4
	ds_write_b16 v190, v4 offset:5168
	v_mul_f32_e32 v4, v22, v36
	v_cvt_pk_bf16_f32 v4, v4, v4
	ds_write_b16 v190, v4 offset:5232
	s_and_saveexec_b64 s[18:19], s[8:9]
	v_cvt_pk_bf16_f32 v4, -v22, -v22
	ds_write_b16 v3, v4 offset:5296
	s_or_b64 exec, exec, s[18:19]
	v_mul_f32_e32 v4, v23, v2
	v_cvt_pk_bf16_f32 v4, v4, v4
	ds_write_b16 v190, v4 offset:5440
	v_mul_f32_e32 v4, v23, v36
	v_cvt_pk_bf16_f32 v4, v4, v4
	ds_write_b16 v190, v4 offset:5504
	s_and_saveexec_b64 s[18:19], s[8:9]
	v_cvt_pk_bf16_f32 v4, -v23, -v23
	ds_write_b16 v3, v4 offset:5568
	s_or_b64 exec, exec, s[18:19]
	v_mul_f32_e32 v4, v24, v2
	v_cvt_pk_bf16_f32 v4, v4, v4
	ds_write_b16 v190, v4 offset:5712
	v_mul_f32_e32 v4, v24, v36
	v_cvt_pk_bf16_f32 v4, v4, v4
	ds_write_b16 v190, v4 offset:5776
	s_and_saveexec_b64 s[18:19], s[8:9]
	v_cvt_pk_bf16_f32 v4, -v24, -v24
	ds_write_b16 v3, v4 offset:5840
	s_or_b64 exec, exec, s[18:19]
	v_mul_f32_e32 v4, v25, v2
	v_cvt_pk_bf16_f32 v4, v4, v4
	ds_write_b16 v190, v4 offset:5984
	v_mul_f32_e32 v4, v25, v36
	v_cvt_pk_bf16_f32 v4, v4, v4
	ds_write_b16 v190, v4 offset:6048
	s_and_saveexec_b64 s[18:19], s[8:9]
	v_cvt_pk_bf16_f32 v4, -v25, -v25
	ds_write_b16 v3, v4 offset:6112
	s_or_b64 exec, exec, s[18:19]
	v_mul_f32_e32 v4, v27, v2
	v_cvt_pk_bf16_f32 v4, v4, v4
	ds_write_b16 v190, v4 offset:6256
	v_mul_f32_e32 v4, v27, v36
	v_cvt_pk_bf16_f32 v4, v4, v4
	ds_write_b16 v190, v4 offset:6320
	s_and_saveexec_b64 s[18:19], s[8:9]
	v_cvt_pk_bf16_f32 v4, -v27, -v27
	ds_write_b16 v3, v4 offset:6384
	s_or_b64 exec, exec, s[18:19]
	v_mul_f32_e32 v4, v28, v2
	v_cvt_pk_bf16_f32 v4, v4, v4
	ds_write_b16 v190, v4 offset:6528
	v_mul_f32_e32 v4, v28, v36
	v_cvt_pk_bf16_f32 v4, v4, v4
	ds_write_b16 v190, v4 offset:6592
	s_and_saveexec_b64 s[18:19], s[8:9]
	v_cvt_pk_bf16_f32 v4, -v28, -v28
	ds_write_b16 v3, v4 offset:6656
	s_or_b64 exec, exec, s[18:19]
	v_mul_f32_e32 v4, v29, v2
	v_cvt_pk_bf16_f32 v4, v4, v4
	ds_write_b16 v190, v4 offset:6800
	v_mul_f32_e32 v4, v29, v36
	v_cvt_pk_bf16_f32 v4, v4, v4
	ds_write_b16 v190, v4 offset:6864
	s_and_saveexec_b64 s[18:19], s[8:9]
	v_cvt_pk_bf16_f32 v4, -v29, -v29
	ds_write_b16 v3, v4 offset:6928
	s_or_b64 exec, exec, s[18:19]
	v_mul_f32_e32 v4, v30, v2
	v_cvt_pk_bf16_f32 v4, v4, v4
	ds_write_b16 v190, v4 offset:7072
	v_mul_f32_e32 v4, v30, v36
	v_cvt_pk_bf16_f32 v4, v4, v4
	ds_write_b16 v190, v4 offset:7136
	s_and_saveexec_b64 s[18:19], s[8:9]
	v_cvt_pk_bf16_f32 v4, -v30, -v30
	ds_write_b16 v3, v4 offset:7200
	s_or_b64 exec, exec, s[18:19]
	v_mul_f32_e32 v4, v31, v2
	v_cvt_pk_bf16_f32 v4, v4, v4
	ds_write_b16 v190, v4 offset:7344
	v_mul_f32_e32 v4, v31, v36
	v_cvt_pk_bf16_f32 v4, v4, v4
	ds_write_b16 v190, v4 offset:7408
	s_and_saveexec_b64 s[18:19], s[8:9]
	v_cvt_pk_bf16_f32 v4, -v31, -v31
	ds_write_b16 v3, v4 offset:7472
	s_or_b64 exec, exec, s[18:19]
	v_mul_f32_e32 v4, v32, v2
	v_cvt_pk_bf16_f32 v4, v4, v4
	ds_write_b16 v190, v4 offset:7616
	v_mul_f32_e32 v4, v32, v36
	v_cvt_pk_bf16_f32 v4, v4, v4
	ds_write_b16 v190, v4 offset:7680
	s_and_saveexec_b64 s[18:19], s[8:9]
	v_cvt_pk_bf16_f32 v4, -v32, -v32
	ds_write_b16 v3, v4 offset:7744
	s_or_b64 exec, exec, s[18:19]
	v_mul_f32_e32 v4, v33, v2
	v_cvt_pk_bf16_f32 v4, v4, v4
	ds_write_b16 v190, v4 offset:7888
	v_mul_f32_e32 v4, v33, v36
	v_cvt_pk_bf16_f32 v4, v4, v4
	ds_write_b16 v190, v4 offset:7952
	s_and_saveexec_b64 s[18:19], s[8:9]
	v_cvt_pk_bf16_f32 v4, -v33, -v33
	ds_write_b16 v3, v4 offset:8016
	s_or_b64 exec, exec, s[18:19]
	v_mul_f32_e32 v4, v34, v2
	v_cvt_pk_bf16_f32 v4, v4, v4
	ds_write_b16 v190, v4 offset:8160
	v_mul_f32_e32 v4, v34, v36
	v_cvt_pk_bf16_f32 v4, v4, v4
	ds_write_b16 v190, v4 offset:8224
	s_and_saveexec_b64 s[18:19], s[8:9]
	v_cvt_pk_bf16_f32 v4, -v34, -v34
	ds_write_b16 v3, v4 offset:8288
	s_or_b64 exec, exec, s[18:19]
	v_mul_f32_e32 v2, v35, v2
	v_cvt_pk_bf16_f32 v2, v2, v2
	ds_write_b16 v190, v2 offset:8432
	v_mul_f32_e32 v2, v35, v36
	v_cvt_pk_bf16_f32 v2, v2, v2
	ds_write_b16 v190, v2 offset:8496
	s_and_saveexec_b64 s[18:19], s[8:9]
	v_cvt_pk_bf16_f32 v2, -v35, -v35
	ds_write_b16 v3, v2 offset:8560
	s_or_b64 exec, exec, s[18:19]
